# s_setprio 2 during MFMA compute phase of GEMM k-loops (prio 0 in LDS-write/wait phase) on top of early-issue + nocg
# speedup vs baseline: 1.0502x; 1.0341x over previous
.LBB0_280:
	s_barrier
	s_waitcnt vmcnt(9)
	ds_write_b128 v186, v[142:145]
	ds_write_b128 v186, v[134:137] offset:4608
	ds_write_b128 v186, v[130:133] offset:9216
	s_waitcnt vmcnt(7)
	ds_write_b128 v186, v[146:149] offset:13824
	ds_write_b128 v186, v[138:141] offset:18432
	s_waitcnt vmcnt(6)
	ds_write_b128 v186, v[150:153] offset:23040
	s_waitcnt vmcnt(5)
	ds_write_b128 v186, v[154:157] offset:27648
	s_waitcnt vmcnt(4)
	ds_write_b128 v186, v[158:161] offset:32256
	s_waitcnt vmcnt(3)
	ds_write_b128 v186, v[162:165] offset:36864
	s_waitcnt vmcnt(2)
	ds_write_b128 v186, v[166:169] offset:41472
	s_waitcnt vmcnt(1)
	ds_write_b128 v186, v[170:173] offset:46080
	s_waitcnt vmcnt(0)
	ds_write_b128 v186, v[174:177] offset:50688
	s_waitcnt lgkmcnt(0)
	s_barrier
	s_setprio 2
	s_mov_b32 vcc_hi, 0
	ds_read_b128 v[244:247], v230
	ds_read_b128 v[210:213], v231 offset:18432
	ds_read_b128 v[248:251], v230 offset:4608
	ds_read_b128 v[214:217], v231 offset:23040
	ds_read_b128 v[218:221], v231 offset:27648
	ds_read_b128 v[222:225], v231 offset:32256
	s_waitcnt lgkmcnt(4)
	v_mfma_f32_32x32x16_bf16 v[114:129], v[210:213], v[244:247], v[114:129]
	s_add_u32 vcc_lo, s22, 0xd400080
	v_lshl_add_u64 v[240:241], v[204:205], 0, vcc
	global_load_dwordx4 v[142:145], v[240:241], off
	ds_read_b128 v[252:255], v230 offset:32
	s_waitcnt lgkmcnt(4)
	v_mfma_f32_32x32x16_bf16 v[82:97], v[210:213], v[248:251], v[82:97]
	s_add_u32 vcc_lo, s22, 0xd410080
	v_lshl_add_u64 v[178:179], v[204:205], 0, vcc
	global_load_dwordx4 v[134:137], v[178:179], off
	ds_read_b128 v[210:213], v231 offset:18464
	s_waitcnt lgkmcnt(4)
	v_mfma_f32_32x32x16_bf16 v[98:113], v[214:217], v[244:247], v[98:113]
	s_add_u32 vcc_lo, s22, 0xd420080
	v_lshl_add_u64 v[240:241], v[204:205], 0, vcc
	global_load_dwordx4 v[130:133], v[240:241], off
	ds_read_b128 v[232:235], v230 offset:4640
	v_mfma_f32_32x32x16_bf16 v[66:81], v[214:217], v[248:251], v[66:81]
	s_add_u32 vcc_lo, s22, 0xd430080
	v_lshl_add_u64 v[178:179], v[204:205], 0, vcc
	global_load_dwordx4 v[146:149], v[178:179], off
	ds_read_b128 v[214:217], v231 offset:23072
	s_waitcnt lgkmcnt(5)
	v_mfma_f32_32x32x16_bf16 v[50:65], v[218:221], v[244:247], v[50:65]
	s_add_u32 vcc_lo, s22, 0xac00080
	v_lshl_add_u64 v[240:241], v[202:203], 0, vcc
	global_load_dwordx4 v[138:141], v[240:241], off
	v_mfma_f32_32x32x16_bf16 v[18:33], v[218:221], v[248:251], v[18:33]
	s_add_u32 vcc_lo, s22, 0xac10080
	v_lshl_add_u64 v[178:179], v[202:203], 0, vcc
	global_load_dwordx4 v[150:153], v[178:179], off
	ds_read_b128 v[218:221], v231 offset:27680
	s_waitcnt lgkmcnt(5)
	v_mfma_f32_32x32x16_bf16 v[34:49], v[222:225], v[244:247], v[34:49]
	s_add_u32 vcc_lo, s22, 0xac20080
	v_lshl_add_u64 v[240:241], v[202:203], 0, vcc
	global_load_dwordx4 v[154:157], v[240:241], off
	v_mfma_f32_32x32x16_bf16 v[2:17], v[222:225], v[248:251], v[2:17]
	s_add_u32 vcc_lo, s22, 0xac30080
	v_lshl_add_u64 v[178:179], v[202:203], 0, vcc
	global_load_dwordx4 v[158:161], v[178:179], off
	ds_read_b128 v[222:225], v231 offset:32288
	s_waitcnt lgkmcnt(4)
	v_mfma_f32_32x32x16_bf16 v[114:129], v[210:213], v[252:255], v[114:129]
	s_add_u32 vcc_lo, s22, 0xac40080
	v_lshl_add_u64 v[240:241], v[202:203], 0, vcc
	global_load_dwordx4 v[162:165], v[240:241], off
	ds_read_b128 v[244:247], v230 offset:64
	s_waitcnt lgkmcnt(4)
	v_mfma_f32_32x32x16_bf16 v[82:97], v[210:213], v[232:235], v[82:97]
	s_add_u32 vcc_lo, s22, 0xac50080
	v_lshl_add_u64 v[178:179], v[202:203], 0, vcc
	global_load_dwordx4 v[166:169], v[178:179], off
	ds_read_b128 v[210:213], v231 offset:18496
	s_waitcnt lgkmcnt(4)
	v_mfma_f32_32x32x16_bf16 v[98:113], v[214:217], v[252:255], v[98:113]
	s_add_u32 vcc_lo, s22, 0xac60080
	v_lshl_add_u64 v[240:241], v[202:203], 0, vcc
	global_load_dwordx4 v[170:173], v[240:241], off
	ds_read_b128 v[248:251], v230 offset:4672
	v_mfma_f32_32x32x16_bf16 v[66:81], v[214:217], v[232:235], v[66:81]
	s_add_u32 vcc_lo, s22, 0xac70080
	v_lshl_add_u64 v[178:179], v[202:203], 0, vcc
	global_load_dwordx4 v[174:177], v[178:179], off
	ds_read_b128 v[214:217], v231 offset:23104
	s_waitcnt lgkmcnt(5)
	v_mfma_f32_32x32x16_bf16 v[50:65], v[218:221], v[252:255], v[50:65]
	v_mfma_f32_32x32x16_bf16 v[18:33], v[218:221], v[232:235], v[18:33]
	ds_read_b128 v[218:221], v231 offset:27712
	s_waitcnt lgkmcnt(5)
	v_mfma_f32_32x32x16_bf16 v[34:49], v[222:225], v[252:255], v[34:49]
	v_mfma_f32_32x32x16_bf16 v[2:17], v[222:225], v[232:235], v[2:17]
	ds_read_b128 v[222:225], v231 offset:32320
	s_waitcnt lgkmcnt(4)
	v_mfma_f32_32x32x16_bf16 v[114:129], v[210:213], v[244:247], v[114:129]
	ds_read_b128 v[252:255], v230 offset:96
	s_waitcnt lgkmcnt(4)
	v_mfma_f32_32x32x16_bf16 v[82:97], v[210:213], v[248:251], v[82:97]
	ds_read_b128 v[210:213], v231 offset:18528
	s_waitcnt lgkmcnt(4)
	v_mfma_f32_32x32x16_bf16 v[98:113], v[214:217], v[244:247], v[98:113]
	ds_read_b128 v[232:235], v230 offset:4704
	v_mfma_f32_32x32x16_bf16 v[66:81], v[214:217], v[248:251], v[66:81]
	ds_read_b128 v[214:217], v231 offset:23136
	s_waitcnt lgkmcnt(5)
	v_mfma_f32_32x32x16_bf16 v[50:65], v[218:221], v[244:247], v[50:65]
	v_mfma_f32_32x32x16_bf16 v[18:33], v[218:221], v[248:251], v[18:33]
	ds_read_b128 v[218:221], v231 offset:27744
	s_waitcnt lgkmcnt(5)
	v_mfma_f32_32x32x16_bf16 v[34:49], v[222:225], v[244:247], v[34:49]
	v_mfma_f32_32x32x16_bf16 v[2:17], v[222:225], v[248:251], v[2:17]
	ds_read_b128 v[222:225], v231 offset:32352
	s_waitcnt lgkmcnt(4)
	v_mfma_f32_32x32x16_bf16 v[114:129], v[210:213], v[252:255], v[114:129]
	s_waitcnt lgkmcnt(3)
	v_mfma_f32_32x32x16_bf16 v[82:97], v[210:213], v[232:235], v[82:97]
	s_waitcnt lgkmcnt(2)
	v_mfma_f32_32x32x16_bf16 v[98:113], v[214:217], v[252:255], v[98:113]
	v_mfma_f32_32x32x16_bf16 v[66:81], v[214:217], v[232:235], v[66:81]
	s_waitcnt lgkmcnt(1)
	v_mfma_f32_32x32x16_bf16 v[50:65], v[218:221], v[252:255], v[50:65]
	v_mfma_f32_32x32x16_bf16 v[18:33], v[218:221], v[232:235], v[18:33]
	s_waitcnt lgkmcnt(0)
	v_mfma_f32_32x32x16_bf16 v[34:49], v[222:225], v[252:255], v[34:49]
	v_mfma_f32_32x32x16_bf16 v[2:17], v[222:225], v[232:235], v[2:17]
	s_setprio 0
	s_add_u32 s22, s22, 0x80
	s_addc_u32 s23, s23, 0
	s_cmpk_eq_i32 s22, 0x780
	s_cbranch_scc0 .LBB0_280
	v_mov_b32_e32 v210, 64
	v_xor_b32_e32 v211, 32, v209
	v_xor_b32_e32 v212, 16, v209
	v_xor_b32_e32 v213, 8, v209
	v_xor_b32_e32 v214, 4, v209
	v_xor_b32_e32 v215, 2, v209
	v_xor_b32_e32 v216, 1, v209
	v_mov_b32_e32 v217, 2
	v_bfrev_b32_e32 v218, 32
	v_bfrev_b32_e32 v219, 64
	v_mov_b32_e32 v220, 0xff800000
	v_mov_b32_e32 v221, 0x80
	v_mov_b32_e32 v222, 0x200
	v_mov_b32_e32 v223, 0x2000
	v_mov_b32_e32 v224, 0x461c4000
	v_mov_b32_e32 v225, 0x63
	v_mov_b64_e32 v[178:179], 0xf500000
	s_barrier
	s_waitcnt vmcnt(11)
	ds_write_b128 v186, v[142:145]
	s_waitcnt vmcnt(10)
	ds_write_b128 v186, v[134:137] offset:4608
	s_waitcnt vmcnt(9)
	ds_write_b128 v186, v[130:133] offset:9216
	s_waitcnt vmcnt(8)
	ds_write_b128 v186, v[146:149] offset:13824
	s_waitcnt vmcnt(7)
	ds_write_b128 v186, v[138:141] offset:18432
	s_waitcnt vmcnt(6)
	ds_write_b128 v186, v[150:153] offset:23040
	s_waitcnt vmcnt(5)
	ds_write_b128 v186, v[154:157] offset:27648
	s_waitcnt vmcnt(4)
	ds_write_b128 v186, v[158:161] offset:32256
	s_waitcnt vmcnt(3)
	ds_write_b128 v186, v[162:165] offset:36864
	s_waitcnt vmcnt(2)
	ds_write_b128 v186, v[166:169] offset:41472
	s_waitcnt vmcnt(1)
	ds_write_b128 v186, v[170:173] offset:46080
	s_waitcnt vmcnt(0)
	ds_write_b128 v186, v[174:177] offset:50688
	s_waitcnt lgkmcnt(0)
	s_barrier
	ds_read_b128 v[130:133], v230 offset:4608
	ds_read_b128 v[134:137], v231 offset:23040
	ds_read_b128 v[138:141], v230
	ds_read_b128 v[142:145], v230 offset:32
	ds_read_b128 v[146:149], v231 offset:18432
	ds_read_b128 v[150:153], v231 offset:18464
	s_waitcnt lgkmcnt(1)
	v_mfma_f32_32x32x16_bf16 v[114:129], v[146:149], v[138:141], v[114:129]
	v_mfma_f32_32x32x16_bf16 v[82:97], v[146:149], v[130:133], v[82:97]
	v_mfma_f32_32x32x16_bf16 v[98:113], v[134:137], v[138:141], v[98:113]
	v_mfma_f32_32x32x16_bf16 v[66:81], v[134:137], v[130:133], v[66:81]
	ds_read_b128 v[134:137], v231 offset:27648
	ds_read_b128 v[146:149], v231 offset:32256
	s_waitcnt lgkmcnt(1)
	v_mfma_f32_32x32x16_bf16 v[50:65], v[134:137], v[138:141], v[50:65]
	v_mfma_f32_32x32x16_bf16 v[18:33], v[134:137], v[130:133], v[18:33]
	s_waitcnt lgkmcnt(0)
	v_mfma_f32_32x32x16_bf16 v[2:17], v[146:149], v[130:133], v[2:17]
	ds_read_b128 v[130:133], v230 offset:4640
	ds_read_b128 v[134:137], v231 offset:23072
	v_mfma_f32_32x32x16_bf16 v[34:49], v[146:149], v[138:141], v[34:49]
	s_waitcnt lgkmcnt(0)
	v_mfma_f32_32x32x16_bf16 v[98:113], v[134:137], v[142:145], v[98:113]
	v_mfma_f32_32x32x16_bf16 v[66:81], v[134:137], v[130:133], v[66:81]
	ds_read_b128 v[134:137], v231 offset:27680
	ds_read_b128 v[138:141], v231 offset:32288
	v_mfma_f32_32x32x16_bf16 v[114:129], v[150:153], v[142:145], v[114:129]
	v_mfma_f32_32x32x16_bf16 v[82:97], v[150:153], v[130:133], v[82:97]
	s_waitcnt lgkmcnt(1)
	v_mfma_f32_32x32x16_bf16 v[50:65], v[134:137], v[142:145], v[50:65]
	v_mfma_f32_32x32x16_bf16 v[18:33], v[134:137], v[130:133], v[18:33]
	s_waitcnt lgkmcnt(0)
	v_mfma_f32_32x32x16_bf16 v[34:49], v[138:141], v[142:145], v[34:49]
	v_mfma_f32_32x32x16_bf16 v[2:17], v[138:141], v[130:133], v[2:17]
	ds_read_b128 v[130:133], v230 offset:64
	ds_read_b128 v[134:137], v230 offset:4672
	ds_read_b128 v[138:141], v231 offset:18496
	ds_read_b128 v[142:145], v231 offset:23104
	s_waitcnt lgkmcnt(1)
	v_mfma_f32_32x32x16_bf16 v[114:129], v[138:141], v[130:133], v[114:129]
	v_mfma_f32_32x32x16_bf16 v[82:97], v[138:141], v[134:137], v[82:97]
	s_waitcnt lgkmcnt(0)
	v_mfma_f32_32x32x16_bf16 v[98:113], v[142:145], v[130:133], v[98:113]
	v_mfma_f32_32x32x16_bf16 v[66:81], v[142:145], v[134:137], v[66:81]
	ds_read_b128 v[138:141], v231 offset:27712
	ds_read_b128 v[142:145], v231 offset:32320
	s_waitcnt lgkmcnt(1)
	v_mfma_f32_32x32x16_bf16 v[50:65], v[138:141], v[130:133], v[50:65]
	v_mfma_f32_32x32x16_bf16 v[18:33], v[138:141], v[134:137], v[18:33]
	s_waitcnt lgkmcnt(0)
	v_mfma_f32_32x32x16_bf16 v[34:49], v[142:145], v[130:133], v[34:49]
	v_mfma_f32_32x32x16_bf16 v[2:17], v[142:145], v[134:137], v[2:17]
	ds_read_b128 v[130:133], v230 offset:96
	ds_read_b128 v[134:137], v230 offset:4704
	ds_read_b128 v[138:141], v231 offset:18528
	ds_read_b128 v[142:145], v231 offset:23136
	s_waitcnt lgkmcnt(1)
	v_mfma_f32_32x32x16_bf16 v[114:129], v[138:141], v[130:133], v[114:129]
	v_mfma_f32_32x32x16_bf16 v[82:97], v[138:141], v[134:137], v[82:97]
	s_waitcnt lgkmcnt(0)
	v_mfma_f32_32x32x16_bf16 v[98:113], v[142:145], v[130:133], v[98:113]
	v_mfma_f32_32x32x16_bf16 v[66:81], v[142:145], v[134:137], v[66:81]
	ds_read_b128 v[138:141], v231 offset:27744
	ds_read_b128 v[142:145], v231 offset:32352
	s_waitcnt lgkmcnt(0)
	s_barrier
	v_mfma_f32_32x32x16_bf16 v[18:33], v[138:141], v[134:137], v[18:33]
	v_mfma_f32_32x32x16_bf16 v[2:17], v[142:145], v[134:137], v[2:17]
	v_add_u32_e32 v136, s2, v187
	v_ashrrev_i32_e32 v134, 11, v136
	v_and_b32_e32 v157, 0x7c0, v136
	v_mfma_f32_32x32x16_bf16 v[50:65], v[138:141], v[130:133], v[50:65]
	v_or_b32_e32 v138, s3, v191
	v_ashrrev_i32_e32 v139, 31, v138
	v_ashrrev_i32_e32 v159, 6, v138
	v_mfma_f32_32x32x16_bf16 v[34:49], v[142:145], v[130:133], v[34:49]
	v_or_b32_e32 v132, v136, v189
	v_ashrrev_i32_e32 v133, 31, v132
	v_lshl_add_u64 v[142:143], v[132:133], 2, s[40:41]
	global_load_dword v132, v[142:143], off
	v_lshlrev_b32_e32 v130, 12, v134
	v_ashrrev_i32_e32 v131, 31, v130
	v_lshl_add_u64 v[130:131], v[130:131], 2, s[42:43]
	v_lshl_add_u64 v[130:131], v[138:139], 2, v[130:131]
	v_lshl_add_u64 v[140:141], v[130:131], 0, v[0:1]
	s_waitcnt vmcnt(0)
	v_fmamk_f32 v132, v132, 0x3a800000, v208
	v_cmp_gt_f32_e32 vcc, s84, v132
	v_mul_f32_e32 v133, 0x4b800000, v132
	s_nop 0
	v_cndmask_b32_e32 v132, v132, v133, vcc
	v_rsq_f32_e32 v132, v132
	s_nop 0
	v_mul_f32_e32 v133, 0x45800000, v132
	v_cndmask_b32_e32 v156, v132, v133, vcc
	global_load_dword v132, v[142:143], off offset:128
	s_waitcnt vmcnt(0)
	v_fmamk_f32 v132, v132, 0x3a800000, v208
	v_cmp_gt_f32_e32 vcc, s84, v132
	v_mul_f32_e32 v133, 0x4b800000, v132
	s_nop 0
	v_cndmask_b32_e32 v132, v132, v133, vcc
	v_rsq_f32_e32 v132, v132
	s_nop 0
	v_mul_f32_e32 v133, 0x45800000, v132
	v_cndmask_b32_e32 v158, v132, v133, vcc
	global_load_dwordx4 v[150:153], v[140:141], off
	global_load_dwordx4 v[160:163], v[140:141], off offset:32
	global_load_dwordx4 v[164:167], v[140:141], off offset:64
	global_load_dwordx4 v[130:133], v[140:141], off offset:96
	global_load_dwordx4 v[168:171], v[140:141], off offset:128
	v_cmp_lt_i32_e32 vcc, 31, v159
	s_waitcnt vmcnt(4)
	v_pk_fma_f32 v[148:149], v[114:115], v[156:157], v[150:151] op_sel_hi:[1,0,1]
	v_pk_fma_f32 v[114:115], v[82:83], v[158:159], v[150:151] op_sel_hi:[1,0,1]
	v_pk_fma_f32 v[150:151], v[116:117], v[156:157], v[152:153] op_sel_hi:[1,0,1]
	v_pk_fma_f32 v[116:117], v[84:85], v[158:159], v[152:153] op_sel_hi:[1,0,1]
	s_waitcnt vmcnt(0)
	v_pk_fma_f32 v[144:145], v[98:99], v[156:157], v[168:169] op_sel_hi:[1,0,1]
	v_pk_fma_f32 v[98:99], v[66:67], v[158:159], v[168:169] op_sel_hi:[1,0,1]
	v_pk_fma_f32 v[146:147], v[100:101], v[156:157], v[170:171] op_sel_hi:[1,0,1]
	v_pk_fma_f32 v[100:101], v[68:69], v[158:159], v[170:171] op_sel_hi:[1,0,1]
	global_load_dwordx4 v[66:69], v[140:141], off offset:160
	v_pk_fma_f32 v[152:153], v[118:119], v[156:157], v[160:161] op_sel_hi:[1,0,1]
	v_pk_fma_f32 v[154:155], v[120:121], v[156:157], v[162:163] op_sel_hi:[1,0,1]
	v_pk_fma_f32 v[122:123], v[122:123], v[156:157], v[164:165] op_sel_hi:[1,0,1]
	v_pk_fma_f32 v[124:125], v[124:125], v[156:157], v[166:167] op_sel_hi:[1,0,1]
	v_pk_fma_f32 v[126:127], v[126:127], v[156:157], v[130:131] op_sel_hi:[1,0,1]
	v_pk_fma_f32 v[84:85], v[94:95], v[158:159], v[130:131] op_sel_hi:[1,0,1]
	v_pk_fma_f32 v[128:129], v[128:129], v[156:157], v[132:133] op_sel_hi:[1,0,1]
	s_waitcnt vmcnt(0)
	v_pk_fma_f32 v[118:119], v[102:103], v[156:157], v[66:67] op_sel_hi:[1,0,1]
	v_pk_fma_f32 v[70:71], v[70:71], v[158:159], v[66:67] op_sel_hi:[1,0,1]
	v_pk_fma_f32 v[120:121], v[104:105], v[156:157], v[68:69] op_sel_hi:[1,0,1]
	v_pk_fma_f32 v[72:73], v[72:73], v[158:159], v[68:69] op_sel_hi:[1,0,1]
	global_load_dwordx4 v[66:69], v[140:141], off offset:192
	v_pk_fma_f32 v[102:103], v[86:87], v[158:159], v[160:161] op_sel_hi:[1,0,1]
	v_pk_fma_f32 v[104:105], v[88:89], v[158:159], v[162:163] op_sel_hi:[1,0,1]
	v_pk_fma_f32 v[88:89], v[90:91], v[158:159], v[164:165] op_sel_hi:[1,0,1]
	v_pk_fma_f32 v[90:91], v[92:93], v[158:159], v[166:167] op_sel_hi:[1,0,1]
	v_pk_fma_f32 v[86:87], v[96:97], v[158:159], v[132:133] op_sel_hi:[1,0,1]
	s_waitcnt vmcnt(0)
	v_pk_fma_f32 v[106:107], v[106:107], v[156:157], v[66:67] op_sel_hi:[1,0,1]
	v_pk_fma_f32 v[66:67], v[74:75], v[158:159], v[66:67] op_sel_hi:[1,0,1]
	v_pk_fma_f32 v[108:109], v[108:109], v[156:157], v[68:69] op_sel_hi:[1,0,1]
	v_pk_fma_f32 v[68:69], v[76:77], v[158:159], v[68:69] op_sel_hi:[1,0,1]
	global_load_dwordx4 v[74:77], v[140:141], off offset:224
	s_waitcnt vmcnt(0)
	v_pk_fma_f32 v[110:111], v[110:111], v[156:157], v[74:75] op_sel_hi:[1,0,1]
	v_pk_fma_f32 v[82:83], v[78:79], v[158:159], v[74:75] op_sel_hi:[1,0,1]
	v_pk_fma_f32 v[94:95], v[112:113], v[156:157], v[76:77] op_sel_hi:[1,0,1]
	v_pk_fma_f32 v[80:81], v[80:81], v[158:159], v[76:77] op_sel_hi:[1,0,1]
	s_and_saveexec_b64 s[2:3], vcc
	s_xor_b64 s[2:3], exec, s[2:3]
	s_cbranch_execz .LBB0_287
	v_cmp_lt_u32_e32 vcc, 47, v159
	v_cvt_pk_bf16_f32 v74, v152, s0
	v_cvt_pk_bf16_f32 v75, v153, s0
	v_cvt_pk_bf16_f32 v76, v154, s0
	v_cvt_pk_bf16_f32 v77, v155, s0
	s_and_saveexec_b64 s[8:9], vcc
	s_xor_b64 s[22:23], exec, s[8:9]
	s_cbranch_execz .LBB0_284
	s_mov_b32 s8, 0x5040100
	v_cvt_pk_bf16_f32 v93, v150, v151
	v_cvt_pk_bf16_f32 v92, v148, v149
	v_perm_b32 v77, v77, v76, s8
	v_perm_b32 v76, v75, v74, s8
	ds_write2_b64 v226, v[92:93], v[76:77] offset1:2
	v_cvt_pk_bf16_f32 v75, v124, v125
	v_cvt_pk_bf16_f32 v74, v122, v123
	v_cvt_pk_bf16_f32 v77, v128, v129
	v_cvt_pk_bf16_f32 v76, v126, v127
	ds_write2_b64 v226, v[74:75], v[76:77] offset0:4 offset1:6
	v_cvt_pk_bf16_f32 v75, v146, v147
	v_cvt_pk_bf16_f32 v74, v144, v145
	v_cvt_pk_bf16_f32 v77, v120, v121
	v_cvt_pk_bf16_f32 v76, v118, v119
	ds_write2_b64 v226, v[74:75], v[76:77] offset0:8 offset1:10
	v_cvt_pk_bf16_f32 v75, v108, v109
	v_cvt_pk_bf16_f32 v74, v106, v107
	v_cvt_pk_bf16_f32 v77, v94, v95
	v_cvt_pk_bf16_f32 v76, v110, v111
	v_ashrrev_i32_e32 v137, 31, v136
	ds_write2_b64 v226, v[74:75], v[76:77] offset0:12 offset1:14
	v_cvt_pk_bf16_f32 v75, v116, v117
	v_cvt_pk_bf16_f32 v74, v114, v115
	v_cvt_pk_bf16_f32 v77, v104, v105
	v_cvt_pk_bf16_f32 v76, v102, v103
	v_add_u32_e32 v92, 0x1000, v226
	v_lshlrev_b64 v[78:79], 11, v[136:137]
	ds_write2_b64 v92, v[74:75], v[76:77] offset0:64 offset1:66
	v_cvt_pk_bf16_f32 v75, v90, v91
	v_cvt_pk_bf16_f32 v74, v88, v89
	v_cvt_pk_bf16_f32 v77, v86, v87
	v_cvt_pk_bf16_f32 v76, v84, v85
	v_lshl_add_u64 v[78:79], s[38:39], 0, v[78:79]
	v_mov_b32_e32 v139, v1
	ds_write2_b64 v92, v[74:75], v[76:77] offset0:68 offset1:70
	v_cvt_pk_bf16_f32 v75, v100, v101
	v_cvt_pk_bf16_f32 v74, v98, v99
	v_cvt_pk_bf16_f32 v73, v72, v73
	v_cvt_pk_bf16_f32 v72, v70, v71
	v_cvt_pk_bf16_f32 v69, v68, v69
	v_cvt_pk_bf16_f32 v68, v66, v67
	v_cvt_pk_bf16_f32 v67, v80, v81
	v_cvt_pk_bf16_f32 v66, v82, v83
	v_lshl_add_u64 v[78:79], v[138:139], 1, v[78:79]
	ds_write2_b64 v92, v[74:75], v[72:73] offset0:72 offset1:74
	ds_write2_b64 v92, v[68:69], v[66:67] offset0:76 offset1:78
	v_lshlrev_b32_e32 v66, 1, v188
	v_mov_b32_e32 v67, v1
	v_lshl_add_u64 v[66:67], v[78:79], 0, v[66:67]
	v_lshlrev_b32_e32 v68, 1, v180
	v_mov_b32_e32 v69, v1
	v_lshl_add_u64 v[74:75], v[66:67], 0, v[68:69]
	ds_read_b128 v[66:69], v227
	ds_read_b128 v[70:73], v227 offset:1152
	s_mov_b32 s8, 0x7ffe000
	v_add_co_u32_e32 v76, vcc, s8, v74
	s_mov_b32 s8, 0x8002000
	s_nop 0
	v_addc_co_u32_e32 v77, vcc, 0, v75, vcc
	s_waitcnt lgkmcnt(1)
	global_store_dwordx4 v[76:77], v[66:69], off offset:2048
	s_nop 1
	v_add_co_u32_e32 v66, vcc, s8, v74
	s_mov_b32 s8, 0x8006000
	s_nop 0
	v_addc_co_u32_e32 v67, vcc, 0, v75, vcc
	s_waitcnt lgkmcnt(0)
	global_store_dwordx4 v[66:67], v[70:73], off offset:2048
	ds_read_b128 v[66:69], v227 offset:2304
	ds_read_b128 v[70:73], v227 offset:3456
	v_add_co_u32_e32 v76, vcc, s8, v74
	s_mov_b32 s8, 0x800a000
	s_nop 0
	v_addc_co_u32_e32 v77, vcc, 0, v75, vcc
	s_waitcnt lgkmcnt(1)
	global_store_dwordx4 v[76:77], v[66:69], off offset:2048
	s_nop 1
	v_add_co_u32_e32 v66, vcc, s8, v74
	s_mov_b32 s8, 0x800e000
	s_nop 0
	v_addc_co_u32_e32 v67, vcc, 0, v75, vcc
	s_waitcnt lgkmcnt(0)
	global_store_dwordx4 v[66:67], v[70:73], off offset:2048
	ds_read_b128 v[66:69], v227 offset:4608
	ds_read_b128 v[70:73], v227 offset:5760
	v_add_co_u32_e32 v76, vcc, s8, v74
	s_nop 1
	v_addc_co_u32_e32 v77, vcc, 0, v75, vcc
	s_waitcnt lgkmcnt(1)
	global_store_dwordx4 v[76:77], v[66:69], off offset:2048
	s_nop 1
	v_add_co_u32_e32 v66, vcc, 0x8012000, v74
	s_nop 1
	v_addc_co_u32_e32 v67, vcc, 0, v75, vcc
	s_waitcnt lgkmcnt(0)
	global_store_dwordx4 v[66:67], v[70:73], off offset:2048
	ds_read_b128 v[66:69], v227 offset:6912
	ds_read_b128 v[70:73], v227 offset:8064
	v_add_co_u32_e32 v76, vcc, 0x8016000, v74
	s_nop 1
	v_addc_co_u32_e32 v77, vcc, 0, v75, vcc
	s_waitcnt lgkmcnt(1)
	global_store_dwordx4 v[76:77], v[66:69], off offset:2048
	s_nop 1
	v_add_co_u32_e32 v66, vcc, 0x801a000, v74
	s_nop 1
	v_addc_co_u32_e32 v67, vcc, 0, v75, vcc
	s_waitcnt lgkmcnt(0)
	global_store_dwordx4 v[66:67], v[70:73], off offset:2048

.LBB0_314:
	s_barrier
	s_waitcnt vmcnt(9)
	ds_write_b128 v186, v[142:145]
	ds_write_b128 v186, v[134:137] offset:4608
	ds_write_b128 v186, v[130:133] offset:9216
	s_waitcnt vmcnt(7)
	ds_write_b128 v186, v[146:149] offset:13824
	ds_write_b128 v186, v[138:141] offset:18432
	s_waitcnt vmcnt(6)
	ds_write_b128 v186, v[150:153] offset:23040
	s_waitcnt vmcnt(5)
	ds_write_b128 v186, v[154:157] offset:27648
	s_waitcnt vmcnt(4)
	ds_write_b128 v186, v[158:161] offset:32256
	s_waitcnt vmcnt(3)
	ds_write_b128 v186, v[162:165] offset:36864
	s_waitcnt vmcnt(2)
	ds_write_b128 v186, v[166:169] offset:41472
	s_waitcnt vmcnt(1)
	ds_write_b128 v186, v[170:173] offset:46080
	s_waitcnt vmcnt(0)
	ds_write_b128 v186, v[174:177] offset:50688
	s_waitcnt lgkmcnt(0)
	s_barrier
	s_setprio 2
	s_mov_b32 vcc_hi, 0
	ds_read_b128 v[244:247], v229
	ds_read_b128 v[210:213], v230 offset:18432
	ds_read_b128 v[248:251], v229 offset:4608
	ds_read_b128 v[214:217], v230 offset:23040
	ds_read_b128 v[218:221], v230 offset:27648
	ds_read_b128 v[222:225], v230 offset:32256
	s_waitcnt lgkmcnt(4)
	v_mfma_f32_32x32x16_bf16 v[114:129], v[210:213], v[244:247], v[114:129]
	s_add_u32 vcc_lo, s22, 0xd400080
	v_lshl_add_u64 v[240:241], v[202:203], 0, vcc
	global_load_dwordx4 v[142:145], v[240:241], off
	ds_read_b128 v[252:255], v229 offset:32
	s_waitcnt lgkmcnt(4)
	v_mfma_f32_32x32x16_bf16 v[98:113], v[210:213], v[248:251], v[98:113]
	s_add_u32 vcc_lo, s22, 0xd410080
	v_lshl_add_u64 v[178:179], v[202:203], 0, vcc
	global_load_dwordx4 v[134:137], v[178:179], off
	ds_read_b128 v[210:213], v230 offset:18464
	s_waitcnt lgkmcnt(4)
	v_mfma_f32_32x32x16_bf16 v[82:97], v[214:217], v[244:247], v[82:97]
	s_add_u32 vcc_lo, s22, 0xd420080
	v_lshl_add_u64 v[240:241], v[202:203], 0, vcc
	global_load_dwordx4 v[130:133], v[240:241], off
	ds_read_b128 v[232:235], v229 offset:4640
	v_mfma_f32_32x32x16_bf16 v[66:81], v[214:217], v[248:251], v[66:81]
	s_add_u32 vcc_lo, s22, 0xd430080
	v_lshl_add_u64 v[178:179], v[202:203], 0, vcc
	global_load_dwordx4 v[146:149], v[178:179], off
	ds_read_b128 v[214:217], v230 offset:23072
	s_waitcnt lgkmcnt(5)
	v_mfma_f32_32x32x16_bf16 v[50:65], v[218:221], v[244:247], v[50:65]
	s_add_u32 vcc_lo, s22, 0xa000080
	v_lshl_add_u64 v[240:241], v[200:201], 0, vcc
	global_load_dwordx4 v[138:141], v[240:241], off
	v_mfma_f32_32x32x16_bf16 v[34:49], v[218:221], v[248:251], v[34:49]
	s_add_u32 vcc_lo, s22, 0xa010080
	v_lshl_add_u64 v[178:179], v[200:201], 0, vcc
	global_load_dwordx4 v[150:153], v[178:179], off
	ds_read_b128 v[218:221], v230 offset:27680
	s_waitcnt lgkmcnt(5)
	v_mfma_f32_32x32x16_bf16 v[18:33], v[222:225], v[244:247], v[18:33]
	s_add_u32 vcc_lo, s22, 0xa020080
	v_lshl_add_u64 v[240:241], v[200:201], 0, vcc
	global_load_dwordx4 v[154:157], v[240:241], off
	v_mfma_f32_32x32x16_bf16 v[2:17], v[222:225], v[248:251], v[2:17]
	s_add_u32 vcc_lo, s22, 0xa030080
	v_lshl_add_u64 v[178:179], v[200:201], 0, vcc
	global_load_dwordx4 v[158:161], v[178:179], off
	ds_read_b128 v[222:225], v230 offset:32288
	s_waitcnt lgkmcnt(4)
	v_mfma_f32_32x32x16_bf16 v[114:129], v[210:213], v[252:255], v[114:129]
	s_add_u32 vcc_lo, s22, 0xa040080
	v_lshl_add_u64 v[240:241], v[200:201], 0, vcc
	global_load_dwordx4 v[162:165], v[240:241], off
	ds_read_b128 v[244:247], v229 offset:64
	s_waitcnt lgkmcnt(4)
	v_mfma_f32_32x32x16_bf16 v[98:113], v[210:213], v[232:235], v[98:113]
	s_add_u32 vcc_lo, s22, 0xa050080
	v_lshl_add_u64 v[178:179], v[200:201], 0, vcc
	global_load_dwordx4 v[166:169], v[178:179], off
	ds_read_b128 v[210:213], v230 offset:18496
	s_waitcnt lgkmcnt(4)
	v_mfma_f32_32x32x16_bf16 v[82:97], v[214:217], v[252:255], v[82:97]
	s_add_u32 vcc_lo, s22, 0xa060080
	v_lshl_add_u64 v[240:241], v[200:201], 0, vcc
	global_load_dwordx4 v[170:173], v[240:241], off
	ds_read_b128 v[248:251], v229 offset:4672
	v_mfma_f32_32x32x16_bf16 v[66:81], v[214:217], v[232:235], v[66:81]
	s_add_u32 vcc_lo, s22, 0xa070080
	v_lshl_add_u64 v[178:179], v[200:201], 0, vcc
	global_load_dwordx4 v[174:177], v[178:179], off
	ds_read_b128 v[214:217], v230 offset:23104
	s_waitcnt lgkmcnt(5)
	v_mfma_f32_32x32x16_bf16 v[50:65], v[218:221], v[252:255], v[50:65]
	v_mfma_f32_32x32x16_bf16 v[34:49], v[218:221], v[232:235], v[34:49]
	ds_read_b128 v[218:221], v230 offset:27712
	s_waitcnt lgkmcnt(5)
	v_mfma_f32_32x32x16_bf16 v[18:33], v[222:225], v[252:255], v[18:33]
	v_mfma_f32_32x32x16_bf16 v[2:17], v[222:225], v[232:235], v[2:17]
	ds_read_b128 v[222:225], v230 offset:32320
	s_waitcnt lgkmcnt(4)
	v_mfma_f32_32x32x16_bf16 v[114:129], v[210:213], v[244:247], v[114:129]
	ds_read_b128 v[252:255], v229 offset:96
	s_waitcnt lgkmcnt(4)
	v_mfma_f32_32x32x16_bf16 v[98:113], v[210:213], v[248:251], v[98:113]
	ds_read_b128 v[210:213], v230 offset:18528
	s_waitcnt lgkmcnt(4)
	v_mfma_f32_32x32x16_bf16 v[82:97], v[214:217], v[244:247], v[82:97]
	ds_read_b128 v[232:235], v229 offset:4704
	v_mfma_f32_32x32x16_bf16 v[66:81], v[214:217], v[248:251], v[66:81]
	ds_read_b128 v[214:217], v230 offset:23136
	s_waitcnt lgkmcnt(5)
	v_mfma_f32_32x32x16_bf16 v[50:65], v[218:221], v[244:247], v[50:65]
	v_mfma_f32_32x32x16_bf16 v[34:49], v[218:221], v[248:251], v[34:49]
	ds_read_b128 v[218:221], v230 offset:27744
	s_waitcnt lgkmcnt(5)
	v_mfma_f32_32x32x16_bf16 v[18:33], v[222:225], v[244:247], v[18:33]
	v_mfma_f32_32x32x16_bf16 v[2:17], v[222:225], v[248:251], v[2:17]
	ds_read_b128 v[222:225], v230 offset:32352
	s_waitcnt lgkmcnt(4)
	v_mfma_f32_32x32x16_bf16 v[114:129], v[210:213], v[252:255], v[114:129]
	s_waitcnt lgkmcnt(3)
	v_mfma_f32_32x32x16_bf16 v[98:113], v[210:213], v[232:235], v[98:113]
	s_waitcnt lgkmcnt(2)
	v_mfma_f32_32x32x16_bf16 v[82:97], v[214:217], v[252:255], v[82:97]
	v_mfma_f32_32x32x16_bf16 v[66:81], v[214:217], v[232:235], v[66:81]
	s_waitcnt lgkmcnt(1)
	v_mfma_f32_32x32x16_bf16 v[50:65], v[218:221], v[252:255], v[50:65]
	v_mfma_f32_32x32x16_bf16 v[34:49], v[218:221], v[232:235], v[34:49]
	s_waitcnt lgkmcnt(0)
	v_mfma_f32_32x32x16_bf16 v[18:33], v[222:225], v[252:255], v[18:33]
	v_mfma_f32_32x32x16_bf16 v[2:17], v[222:225], v[232:235], v[2:17]
	s_setprio 0
	s_add_u32 s22, s22, 0x80
	s_addc_u32 s23, s23, 0
	s_cmpk_eq_i32 s22, 0x780
	s_cbranch_scc0 .LBB0_314
	v_mov_b32_e32 v210, 64
	v_xor_b32_e32 v211, 32, v209
	v_xor_b32_e32 v212, 16, v209
	v_xor_b32_e32 v213, 8, v209
	v_xor_b32_e32 v214, 4, v209
	v_xor_b32_e32 v215, 2, v209
	v_xor_b32_e32 v216, 1, v209
	v_mov_b32_e32 v217, 2
	v_bfrev_b32_e32 v218, 32
	v_bfrev_b32_e32 v219, 64
	v_mov_b32_e32 v220, 0xff800000
	v_mov_b32_e32 v221, 0x80
	v_mov_b32_e32 v222, 0x200
	v_mov_b32_e32 v223, 0x2000
	v_mov_b32_e32 v224, 0x461c4000
	v_mov_b32_e32 v225, 0x63
	v_mov_b64_e32 v[178:179], 0xf500000
	s_barrier
	s_waitcnt vmcnt(11)
	ds_write_b128 v186, v[142:145]
	s_waitcnt vmcnt(10)
	ds_write_b128 v186, v[134:137] offset:4608
	s_waitcnt vmcnt(9)
	ds_write_b128 v186, v[130:133] offset:9216
	s_waitcnt vmcnt(8)
	ds_write_b128 v186, v[146:149] offset:13824
	s_waitcnt vmcnt(7)
	ds_write_b128 v186, v[138:141] offset:18432
	s_waitcnt vmcnt(6)
	ds_write_b128 v186, v[150:153] offset:23040
	s_waitcnt vmcnt(5)
	ds_write_b128 v186, v[154:157] offset:27648
	s_waitcnt vmcnt(4)
	ds_write_b128 v186, v[158:161] offset:32256
	s_waitcnt vmcnt(3)
	ds_write_b128 v186, v[162:165] offset:36864
	s_waitcnt vmcnt(2)
	ds_write_b128 v186, v[166:169] offset:41472
	s_waitcnt vmcnt(1)
	ds_write_b128 v186, v[170:173] offset:46080
	s_waitcnt vmcnt(0)
	ds_write_b128 v186, v[174:177] offset:50688
	s_waitcnt lgkmcnt(0)
	s_barrier
	ds_read_b128 v[130:133], v230 offset:18432
	ds_read_b128 v[134:137], v229
	ds_read_b128 v[138:141], v229 offset:32
	ds_read_b128 v[142:145], v230 offset:18464
	ds_read_b128 v[146:149], v229 offset:4608
	ds_read_b128 v[150:153], v229 offset:4640
	s_waitcnt lgkmcnt(4)
	v_mfma_f32_32x32x16_bf16 v[114:129], v[130:133], v[134:137], v[114:129]
	v_add_u32_e32 v170, s2, v187
	v_or_b32_e32 v168, s3, v204
	v_ashrrev_i32_e32 v172, 11, v170
	v_ashrrev_i32_e32 v173, 6, v168
	v_lshlrev_b32_e32 v174, 12, v172
	v_or_b32_e32 v166, v170, v189
	v_and_b32_e32 v200, 0x7c0, v170
	s_waitcnt lgkmcnt(1)
	v_mfma_f32_32x32x16_bf16 v[98:113], v[130:133], v[146:149], v[98:113]
	ds_read_b128 v[130:133], v230 offset:23040
	ds_read_b128 v[154:157], v230 offset:23072
	v_cmp_gt_i32_e32 vcc, 47, v173
	v_ashrrev_i32_e32 v169, 31, v168
	v_ashrrev_i32_e32 v175, 31, v174
	v_ashrrev_i32_e32 v167, 31, v166
	v_lshlrev_b32_e32 v0, 2, v188
	s_waitcnt lgkmcnt(1)
	v_mfma_f32_32x32x16_bf16 v[82:97], v[130:133], v[134:137], v[82:97]
	v_mfma_f32_32x32x16_bf16 v[66:81], v[130:133], v[146:149], v[66:81]
	ds_read_b128 v[130:133], v230 offset:27648
	ds_read_b128 v[158:161], v230 offset:27680
	s_waitcnt lgkmcnt(1)
	v_mfma_f32_32x32x16_bf16 v[50:65], v[130:133], v[134:137], v[50:65]
	v_mfma_f32_32x32x16_bf16 v[34:49], v[130:133], v[146:149], v[34:49]
	ds_read_b128 v[130:133], v230 offset:32256
	ds_read_b128 v[162:165], v230 offset:32288
	s_waitcnt lgkmcnt(1)
	v_mfma_f32_32x32x16_bf16 v[18:33], v[130:133], v[134:137], v[18:33]
	v_mfma_f32_32x32x16_bf16 v[2:17], v[130:133], v[146:149], v[2:17]
	v_mfma_f32_32x32x16_bf16 v[114:129], v[142:145], v[138:141], v[114:129]
	v_mfma_f32_32x32x16_bf16 v[98:113], v[142:145], v[150:153], v[98:113]
	v_mfma_f32_32x32x16_bf16 v[82:97], v[154:157], v[138:141], v[82:97]
	v_mfma_f32_32x32x16_bf16 v[66:81], v[154:157], v[150:153], v[66:81]
	v_mfma_f32_32x32x16_bf16 v[50:65], v[158:161], v[138:141], v[50:65]
	v_mfma_f32_32x32x16_bf16 v[34:49], v[158:161], v[150:153], v[34:49]
	s_waitcnt lgkmcnt(0)
	v_mfma_f32_32x32x16_bf16 v[18:33], v[162:165], v[138:141], v[18:33]
	ds_read_b128 v[130:133], v230 offset:18496
	ds_read_b128 v[134:137], v229 offset:64
	ds_read_b128 v[138:141], v229 offset:96
	ds_read_b128 v[142:145], v230 offset:18528
	v_mfma_f32_32x32x16_bf16 v[2:17], v[162:165], v[150:153], v[2:17]
	ds_read_b128 v[146:149], v229 offset:4672
	ds_read_b128 v[150:153], v229 offset:4704
	s_waitcnt lgkmcnt(4)
	v_mfma_f32_32x32x16_bf16 v[114:129], v[130:133], v[134:137], v[114:129]
	s_waitcnt lgkmcnt(1)
	v_mfma_f32_32x32x16_bf16 v[98:113], v[130:133], v[146:149], v[98:113]
	ds_read_b128 v[130:133], v230 offset:23104
	ds_read_b128 v[154:157], v230 offset:23136
	s_waitcnt lgkmcnt(1)
	v_mfma_f32_32x32x16_bf16 v[82:97], v[130:133], v[134:137], v[82:97]
	v_mfma_f32_32x32x16_bf16 v[66:81], v[130:133], v[146:149], v[66:81]
	ds_read_b128 v[130:133], v230 offset:27712
	ds_read_b128 v[158:161], v230 offset:27744
	s_waitcnt lgkmcnt(1)
	v_mfma_f32_32x32x16_bf16 v[50:65], v[130:133], v[134:137], v[50:65]
	v_mfma_f32_32x32x16_bf16 v[34:49], v[130:133], v[146:149], v[34:49]
	ds_read_b128 v[130:133], v230 offset:32320
	ds_read_b128 v[162:165], v230 offset:32352
	s_waitcnt lgkmcnt(0)
	s_barrier
	v_mfma_f32_32x32x16_bf16 v[18:33], v[130:133], v[134:137], v[18:33]
	v_mfma_f32_32x32x16_bf16 v[2:17], v[130:133], v[146:149], v[2:17]
	v_mfma_f32_32x32x16_bf16 v[114:129], v[142:145], v[138:141], v[114:129]
	v_mfma_f32_32x32x16_bf16 v[98:113], v[142:145], v[150:153], v[98:113]
	v_mfma_f32_32x32x16_bf16 v[82:97], v[154:157], v[138:141], v[82:97]
	v_mfma_f32_32x32x16_bf16 v[66:81], v[154:157], v[150:153], v[66:81]
	v_mfma_f32_32x32x16_bf16 v[50:65], v[158:161], v[138:141], v[50:65]
	v_mfma_f32_32x32x16_bf16 v[34:49], v[158:161], v[150:153], v[34:49]
	v_mfma_f32_32x32x16_bf16 v[18:33], v[162:165], v[138:141], v[18:33]
	v_mfma_f32_32x32x16_bf16 v[2:17], v[162:165], v[150:153], v[2:17]
	s_and_saveexec_b64 s[54:55], vcc
	s_cbranch_execz .LBB0_370
	v_lshl_add_u64 v[130:131], v[174:175], 2, s[42:43]
	v_lshl_add_u64 v[130:131], v[168:169], 2, v[130:131]
	v_lshl_add_u64 v[132:133], v[166:167], 2, s[40:41]
	v_lshl_add_u64 v[130:131], v[130:131], 0, v[0:1]
	global_load_dword v163, v[132:133], off
	global_load_dword v162, v[132:133], off offset:128
	global_load_dwordx4 v[158:161], v[130:131], off
	global_load_dwordx4 v[154:157], v[130:131], off offset:32
	global_load_dwordx4 v[150:153], v[130:131], off offset:64
	global_load_dwordx4 v[146:149], v[130:131], off offset:96
	global_load_dwordx4 v[142:145], v[130:131], off offset:128
	global_load_dwordx4 v[138:141], v[130:131], off offset:160
	global_load_dwordx4 v[134:137], v[130:131], off offset:192
	s_nop 0
	global_load_dwordx4 v[130:133], v[130:131], off offset:224
	v_cmp_lt_i32_e32 vcc, 7, v173
	s_and_saveexec_b64 s[2:3], vcc
	s_xor_b64 s[60:61], exec, s[2:3]
	s_cbranch_execz .LBB0_356
	s_movk_i32 s2, 0x200
	v_cmp_ne_u32_e32 vcc, s2, v168
	s_and_saveexec_b64 s[2:3], vcc
	s_xor_b64 s[2:3], exec, s[2:3]
	s_cbranch_execz .LBB0_353
	v_cmp_lt_u32_e32 vcc, 17, v173
	s_and_saveexec_b64 s[6:7], vcc
	s_xor_b64 s[62:63], exec, s[6:7]
	s_cbranch_execz .LBB0_350
	v_cmp_lt_u32_e32 vcc, 25, v173
	s_and_saveexec_b64 s[6:7], vcc
	s_xor_b64 s[64:65], exec, s[6:7]
	s_cbranch_execz .LBB0_347
	v_cmp_lt_u32_e32 vcc, 27, v173
	s_and_saveexec_b64 s[6:7], vcc
	s_xor_b64 s[66:67], exec, s[6:7]
	s_cbranch_execz .LBB0_344
	v_cmp_lt_u32_e32 vcc, 29, v173
	s_and_saveexec_b64 s[6:7], vcc
	s_xor_b64 s[68:69], exec, s[6:7]
	s_cbranch_execz .LBB0_341
	v_cmp_lt_u32_e32 vcc, 31, v173
	s_and_saveexec_b64 s[6:7], vcc
	s_xor_b64 s[70:71], exec, s[6:7]
	s_cbranch_execz .LBB0_338
	v_cmp_lt_u32_e32 vcc, 33, v173
	s_and_saveexec_b64 s[6:7], vcc
	s_xor_b64 s[72:73], exec, s[6:7]
	s_cbranch_execz .LBB0_335
	v_cmp_lt_u32_e32 vcc, 35, v173
	s_and_saveexec_b64 s[6:7], vcc
	s_xor_b64 s[58:59], exec, s[6:7]
	s_cbranch_execz .LBB0_332
	v_cmp_lt_u32_e32 vcc, 37, v173
	s_and_saveexec_b64 s[6:7], vcc
	s_xor_b64 s[22:23], exec, s[6:7]
	s_cbranch_execz .LBB0_329
	s_movk_i32 s6, 0xb80
	v_cmp_ne_u32_e32 vcc, s6, v168
	v_mov_b32_e32 v171, 0
	v_mov_b64_e32 v[176:177], 0
	s_mov_b64 s[56:57], 0
	s_and_saveexec_b64 s[74:75], vcc
	s_cbranch_execz .LBB0_328
	v_ashrrev_i32_e32 v171, 31, v170
	v_lshlrev_b64 v[164:165], 10, v[170:171]
	v_lshl_add_u64 v[164:165], s[38:39], 0, v[164:165]
	v_mov_b32_e32 v176, v168
	v_mov_b32_e32 v177, v1
	v_lshl_add_u64 v[164:165], v[176:177], 1, v[164:165]
	s_mov_b64 s[6:7], 0x4ffed00
	s_mov_b64 s[56:57], exec
	v_lshl_add_u64 v[176:177], v[164:165], 0, s[6:7]
	v_mov_b32_e32 v171, 0x200

.LBB0_1003:
	s_barrier
	s_waitcnt vmcnt(9)
	ds_write_b128 v184, v[134:137]
	ds_write_b128 v184, v[142:145] offset:4608
	s_waitcnt vmcnt(8)
	ds_write_b128 v184, v[138:141] offset:9216
	s_waitcnt vmcnt(7)
	ds_write_b128 v184, v[150:153] offset:13824
	ds_write_b128 v184, v[130:133] offset:18432
	s_waitcnt vmcnt(6)
	ds_write_b128 v184, v[146:149] offset:23040
	s_waitcnt vmcnt(5)
	ds_write_b128 v184, v[154:157] offset:27648
	s_waitcnt vmcnt(4)
	ds_write_b128 v184, v[158:161] offset:32256
	s_waitcnt vmcnt(3)
	ds_write_b128 v184, v[162:165] offset:36864
	s_waitcnt vmcnt(2)
	ds_write_b128 v184, v[166:169] offset:41472
	s_waitcnt vmcnt(1)
	ds_write_b128 v184, v[170:173] offset:46080
	s_waitcnt vmcnt(0)
	ds_write_b128 v184, v[174:177] offset:50688
	s_waitcnt lgkmcnt(0)
	s_barrier
	s_setprio 2
	s_mov_b32 vcc_hi, 0
	ds_read_b128 v[244:247], v227
	ds_read_b128 v[210:213], v228 offset:18432
	ds_read_b128 v[248:251], v227 offset:4608
	ds_read_b128 v[214:217], v228 offset:23040
	ds_read_b128 v[218:221], v228 offset:27648
	ds_read_b128 v[222:225], v228 offset:32256
	s_waitcnt lgkmcnt(4)
	v_mfma_f32_32x32x16_bf16 v[114:129], v[210:213], v[244:247], v[114:129]
	s_add_u32 vcc_lo, s22, 0x80
	v_lshl_add_u64 v[238:239], v[194:195], 0, vcc
	global_load_dwordx4 v[130:133], v[238:239], off
	ds_read_b128 v[252:255], v227 offset:32
	s_waitcnt lgkmcnt(4)
	v_mfma_f32_32x32x16_bf16 v[82:97], v[210:213], v[248:251], v[82:97]
	s_add_u32 vcc_lo, s22, 0x80
	v_lshl_add_u64 v[178:179], v[192:193], 0, vcc
	global_load_dwordx4 v[134:137], v[178:179], off
	ds_read_b128 v[210:213], v228 offset:18464
	s_waitcnt lgkmcnt(4)
	v_mfma_f32_32x32x16_bf16 v[98:113], v[214:217], v[244:247], v[98:113]
	s_add_u32 vcc_lo, s22, 0x10080
	v_lshl_add_u64 v[238:239], v[192:193], 0, vcc
	global_load_dwordx4 v[142:145], v[238:239], off
	ds_read_b128 v[230:233], v227 offset:4640
	v_mfma_f32_32x32x16_bf16 v[66:81], v[214:217], v[248:251], v[66:81]
	s_add_u32 vcc_lo, s22, 0x20080
	v_lshl_add_u64 v[178:179], v[192:193], 0, vcc
	global_load_dwordx4 v[138:141], v[178:179], off
	ds_read_b128 v[214:217], v228 offset:23072
	s_waitcnt lgkmcnt(5)
	v_mfma_f32_32x32x16_bf16 v[50:65], v[218:221], v[244:247], v[50:65]
	s_add_u32 vcc_lo, s22, 0x30080
	v_lshl_add_u64 v[238:239], v[192:193], 0, vcc
	global_load_dwordx4 v[150:153], v[238:239], off
	v_mfma_f32_32x32x16_bf16 v[18:33], v[218:221], v[248:251], v[18:33]
	s_add_u32 vcc_lo, s22, 0x10080
	v_lshl_add_u64 v[178:179], v[194:195], 0, vcc
	global_load_dwordx4 v[146:149], v[178:179], off
	ds_read_b128 v[218:221], v228 offset:27680
	s_waitcnt lgkmcnt(5)
	v_mfma_f32_32x32x16_bf16 v[34:49], v[222:225], v[244:247], v[34:49]
	s_add_u32 vcc_lo, s22, 0x20080
	v_lshl_add_u64 v[238:239], v[194:195], 0, vcc
	global_load_dwordx4 v[154:157], v[238:239], off
	v_mfma_f32_32x32x16_bf16 v[2:17], v[222:225], v[248:251], v[2:17]
	s_add_u32 vcc_lo, s22, 0x30080
	v_lshl_add_u64 v[178:179], v[194:195], 0, vcc
	global_load_dwordx4 v[158:161], v[178:179], off
	ds_read_b128 v[222:225], v228 offset:32288
	s_waitcnt lgkmcnt(4)
	v_mfma_f32_32x32x16_bf16 v[114:129], v[210:213], v[252:255], v[114:129]
	s_add_u32 vcc_lo, s22, 0x40080
	v_lshl_add_u64 v[238:239], v[194:195], 0, vcc
	global_load_dwordx4 v[162:165], v[238:239], off
	ds_read_b128 v[244:247], v227 offset:64
	s_waitcnt lgkmcnt(4)
	v_mfma_f32_32x32x16_bf16 v[82:97], v[210:213], v[230:233], v[82:97]
	s_add_u32 vcc_lo, s22, 0x50080
	v_lshl_add_u64 v[178:179], v[194:195], 0, vcc
	global_load_dwordx4 v[166:169], v[178:179], off
	ds_read_b128 v[210:213], v228 offset:18496
	s_waitcnt lgkmcnt(4)
	v_mfma_f32_32x32x16_bf16 v[98:113], v[214:217], v[252:255], v[98:113]
	s_add_u32 vcc_lo, s22, 0x60080
	v_lshl_add_u64 v[238:239], v[194:195], 0, vcc
	global_load_dwordx4 v[170:173], v[238:239], off
	ds_read_b128 v[248:251], v227 offset:4672
	v_mfma_f32_32x32x16_bf16 v[66:81], v[214:217], v[230:233], v[66:81]
	s_add_u32 vcc_lo, s22, 0x70080
	v_lshl_add_u64 v[178:179], v[194:195], 0, vcc
	global_load_dwordx4 v[174:177], v[178:179], off
	ds_read_b128 v[214:217], v228 offset:23104
	s_waitcnt lgkmcnt(5)
	v_mfma_f32_32x32x16_bf16 v[50:65], v[218:221], v[252:255], v[50:65]
	v_mfma_f32_32x32x16_bf16 v[18:33], v[218:221], v[230:233], v[18:33]
	ds_read_b128 v[218:221], v228 offset:27712
	s_waitcnt lgkmcnt(5)
	v_mfma_f32_32x32x16_bf16 v[34:49], v[222:225], v[252:255], v[34:49]
	v_mfma_f32_32x32x16_bf16 v[2:17], v[222:225], v[230:233], v[2:17]
	ds_read_b128 v[222:225], v228 offset:32320
	s_waitcnt lgkmcnt(4)
	v_mfma_f32_32x32x16_bf16 v[114:129], v[210:213], v[244:247], v[114:129]
	ds_read_b128 v[252:255], v227 offset:96
	s_waitcnt lgkmcnt(4)
	v_mfma_f32_32x32x16_bf16 v[82:97], v[210:213], v[248:251], v[82:97]
	ds_read_b128 v[210:213], v228 offset:18528
	s_waitcnt lgkmcnt(4)
	v_mfma_f32_32x32x16_bf16 v[98:113], v[214:217], v[244:247], v[98:113]
	ds_read_b128 v[230:233], v227 offset:4704
	v_mfma_f32_32x32x16_bf16 v[66:81], v[214:217], v[248:251], v[66:81]
	ds_read_b128 v[214:217], v228 offset:23136
	s_waitcnt lgkmcnt(5)
	v_mfma_f32_32x32x16_bf16 v[50:65], v[218:221], v[244:247], v[50:65]
	v_mfma_f32_32x32x16_bf16 v[18:33], v[218:221], v[248:251], v[18:33]
	ds_read_b128 v[218:221], v228 offset:27744
	s_waitcnt lgkmcnt(5)
	v_mfma_f32_32x32x16_bf16 v[34:49], v[222:225], v[244:247], v[34:49]
	v_mfma_f32_32x32x16_bf16 v[2:17], v[222:225], v[248:251], v[2:17]
	ds_read_b128 v[222:225], v228 offset:32352
	s_waitcnt lgkmcnt(4)
	v_mfma_f32_32x32x16_bf16 v[114:129], v[210:213], v[252:255], v[114:129]
	s_waitcnt lgkmcnt(3)
	v_mfma_f32_32x32x16_bf16 v[82:97], v[210:213], v[230:233], v[82:97]
	s_waitcnt lgkmcnt(2)
	v_mfma_f32_32x32x16_bf16 v[98:113], v[214:217], v[252:255], v[98:113]
	v_mfma_f32_32x32x16_bf16 v[66:81], v[214:217], v[230:233], v[66:81]
	s_waitcnt lgkmcnt(1)
	v_mfma_f32_32x32x16_bf16 v[50:65], v[218:221], v[252:255], v[50:65]
	v_mfma_f32_32x32x16_bf16 v[18:33], v[218:221], v[230:233], v[18:33]
	s_waitcnt lgkmcnt(0)
	v_mfma_f32_32x32x16_bf16 v[34:49], v[222:225], v[252:255], v[34:49]
	v_mfma_f32_32x32x16_bf16 v[2:17], v[222:225], v[230:233], v[2:17]
	s_setprio 0
	s_add_u32 s22, s22, 0x80
	s_addc_u32 s23, s23, 0
	s_cmpk_eq_i32 s22, 0x780
	s_cbranch_scc0 .LBB0_1003
	v_mov_b32_e32 v210, 64
	v_xor_b32_e32 v211, 32, v209
	v_xor_b32_e32 v212, 16, v209
	v_xor_b32_e32 v213, 8, v209
	v_xor_b32_e32 v214, 4, v209
	v_xor_b32_e32 v215, 2, v209
	v_xor_b32_e32 v216, 1, v209
	v_mov_b32_e32 v217, 2
	v_bfrev_b32_e32 v218, 32
	v_bfrev_b32_e32 v219, 64
	v_mov_b32_e32 v220, 0xff800000
	v_mov_b32_e32 v221, 0x80
	v_mov_b32_e32 v222, 0x200
	v_mov_b32_e32 v223, 0x2000
	v_mov_b32_e32 v224, 0x461c4000
	v_mov_b32_e32 v225, 0x63
	v_mov_b64_e32 v[178:179], 0xf500000
	s_barrier
	s_waitcnt vmcnt(10)
	ds_write_b128 v184, v[134:137]
	s_waitcnt vmcnt(9)
	ds_write_b128 v184, v[142:145] offset:4608
	s_waitcnt vmcnt(8)
	ds_write_b128 v184, v[138:141] offset:9216
	s_waitcnt vmcnt(7)
	ds_write_b128 v184, v[150:153] offset:13824
	ds_write_b128 v184, v[130:133] offset:18432
	s_waitcnt vmcnt(6)
	ds_write_b128 v184, v[146:149] offset:23040
	s_waitcnt vmcnt(5)
	ds_write_b128 v184, v[154:157] offset:27648
	s_waitcnt vmcnt(4)
	ds_write_b128 v184, v[158:161] offset:32256
	s_waitcnt vmcnt(3)
	ds_write_b128 v184, v[162:165] offset:36864
	s_waitcnt vmcnt(2)
	ds_write_b128 v184, v[166:169] offset:41472
	s_waitcnt vmcnt(1)
	ds_write_b128 v184, v[170:173] offset:46080
	s_waitcnt vmcnt(0)
	ds_write_b128 v184, v[174:177] offset:50688
	s_waitcnt lgkmcnt(0)
	s_barrier
	ds_read_b128 v[130:133], v227 offset:4608
	ds_read_b128 v[134:137], v228 offset:23040
	ds_read_b128 v[138:141], v227
	ds_read_b128 v[142:145], v227 offset:32
	ds_read_b128 v[146:149], v228 offset:18432
	ds_read_b128 v[150:153], v228 offset:18464
	s_waitcnt lgkmcnt(1)
	v_mfma_f32_32x32x16_bf16 v[114:129], v[146:149], v[138:141], v[114:129]
	v_add_u32_e32 v166, s2, v185
	v_or_b32_e32 v168, v166, v198
	v_ashrrev_i32_e32 v169, 31, v168
	v_cndmask_b32_e64 v167, 0, 1, s[42:43]
	v_cmp_ne_u32_e64 s[40:41], 1, v167
	s_andn2_b64 vcc, exec, s[42:43]
	v_mfma_f32_32x32x16_bf16 v[82:97], v[146:149], v[130:133], v[82:97]
	v_mfma_f32_32x32x16_bf16 v[98:113], v[134:137], v[138:141], v[98:113]
	v_mfma_f32_32x32x16_bf16 v[66:81], v[134:137], v[130:133], v[66:81]
	ds_read_b128 v[134:137], v228 offset:27648
	ds_read_b128 v[146:149], v228 offset:32256
	s_waitcnt lgkmcnt(1)
	v_mfma_f32_32x32x16_bf16 v[50:65], v[134:137], v[138:141], v[50:65]
	v_mfma_f32_32x32x16_bf16 v[18:33], v[134:137], v[130:133], v[18:33]
	s_waitcnt lgkmcnt(0)
	v_mfma_f32_32x32x16_bf16 v[2:17], v[146:149], v[130:133], v[2:17]
	ds_read_b128 v[130:133], v227 offset:4640
	ds_read_b128 v[134:137], v228 offset:23072
	v_mfma_f32_32x32x16_bf16 v[34:49], v[146:149], v[138:141], v[34:49]
	s_waitcnt lgkmcnt(0)
	v_mfma_f32_32x32x16_bf16 v[98:113], v[134:137], v[142:145], v[98:113]
	v_mfma_f32_32x32x16_bf16 v[66:81], v[134:137], v[130:133], v[66:81]
	ds_read_b128 v[134:137], v228 offset:27680
	ds_read_b128 v[138:141], v228 offset:32288
	v_mfma_f32_32x32x16_bf16 v[114:129], v[150:153], v[142:145], v[114:129]
	v_mfma_f32_32x32x16_bf16 v[82:97], v[150:153], v[130:133], v[82:97]
	v_lshlrev_b64 v[150:151], 10, v[168:169]
	s_waitcnt lgkmcnt(1)
	v_mfma_f32_32x32x16_bf16 v[50:65], v[134:137], v[142:145], v[50:65]
	v_mfma_f32_32x32x16_bf16 v[18:33], v[134:137], v[130:133], v[18:33]
	s_waitcnt lgkmcnt(0)
	v_mfma_f32_32x32x16_bf16 v[34:49], v[138:141], v[142:145], v[34:49]
	v_mfma_f32_32x32x16_bf16 v[2:17], v[138:141], v[130:133], v[2:17]
	ds_read_b128 v[130:133], v227 offset:64
	ds_read_b128 v[134:137], v227 offset:4672
	ds_read_b128 v[138:141], v228 offset:18496
	ds_read_b128 v[142:145], v228 offset:23104
	s_waitcnt lgkmcnt(1)
	v_mfma_f32_32x32x16_bf16 v[114:129], v[138:141], v[130:133], v[114:129]
	v_mfma_f32_32x32x16_bf16 v[82:97], v[138:141], v[134:137], v[82:97]
	s_waitcnt lgkmcnt(0)
	v_mfma_f32_32x32x16_bf16 v[98:113], v[142:145], v[130:133], v[98:113]
	v_mfma_f32_32x32x16_bf16 v[66:81], v[142:145], v[134:137], v[66:81]
	ds_read_b128 v[138:141], v228 offset:27712
	ds_read_b128 v[142:145], v228 offset:32320
	s_waitcnt lgkmcnt(1)
	v_mfma_f32_32x32x16_bf16 v[50:65], v[138:141], v[130:133], v[50:65]
	v_mfma_f32_32x32x16_bf16 v[18:33], v[138:141], v[134:137], v[18:33]
	s_waitcnt lgkmcnt(0)
	v_mfma_f32_32x32x16_bf16 v[34:49], v[142:145], v[130:133], v[34:49]
	v_mfma_f32_32x32x16_bf16 v[2:17], v[142:145], v[134:137], v[2:17]
	ds_read_b128 v[130:133], v227 offset:96
	ds_read_b128 v[134:137], v227 offset:4704
	ds_read_b128 v[138:141], v228 offset:18528
	ds_read_b128 v[142:145], v228 offset:23136
	s_waitcnt lgkmcnt(1)
	v_mfma_f32_32x32x16_bf16 v[114:129], v[138:141], v[130:133], v[114:129]
	v_mfma_f32_32x32x16_bf16 v[82:97], v[138:141], v[134:137], v[82:97]
	s_waitcnt lgkmcnt(0)
	v_mfma_f32_32x32x16_bf16 v[98:113], v[142:145], v[130:133], v[98:113]
	v_mfma_f32_32x32x16_bf16 v[66:81], v[142:145], v[134:137], v[66:81]
	ds_read_b128 v[138:141], v228 offset:27744
	ds_read_b128 v[142:145], v228 offset:32352
	s_waitcnt lgkmcnt(0)
	s_barrier
	v_mfma_f32_32x32x16_bf16 v[50:65], v[138:141], v[130:133], v[50:65]
	v_mfma_f32_32x32x16_bf16 v[34:49], v[142:145], v[130:133], v[34:49]
	v_ashrrev_i32_e32 v132, 11, v166
	v_add_u32_e32 v0, s8, v132
	v_mov_b64_e32 v[130:131], s[46:47]
	v_mfma_f32_32x32x16_bf16 v[18:33], v[138:141], v[134:137], v[18:33]
	v_or_b32_e32 v138, s3, v197
	v_mad_i64_i32 v[130:131], s[2:3], v0, s20, v[130:131]
	s_mov_b64 s[2:3], 0xc902000
	v_ashrrev_i32_e32 v139, 31, v138
	v_lshl_add_u64 v[140:141], v[130:131], 0, s[2:3]
	v_lshlrev_b32_e32 v0, 2, v186
	v_mfma_f32_32x32x16_bf16 v[2:17], v[142:145], v[134:137], v[2:17]
	v_lshlrev_b64 v[144:145], 2, v[138:139]
	v_lshl_add_u64 v[130:131], v[140:141], 0, v[144:145]
	v_lshl_add_u64 v[130:131], v[130:131], 0, v[0:1]
	global_load_dwordx4 v[134:137], v[130:131], off
	v_lshlrev_b32_e32 v130, 10, v132
	v_ashrrev_i32_e32 v131, 31, v130
	v_lshl_add_u64 v[130:131], v[130:131], 2, s[36:37]
	v_lshl_add_u64 v[130:131], v[130:131], 0, v[144:145]
	v_lshl_add_u64 v[142:143], v[130:131], 0, v[0:1]
	global_load_dwordx4 v[130:133], v[142:143], off
	ds_write_b128 v199, v[114:117]
	ds_write_b128 v199, v[118:121] offset:32
	ds_write_b128 v199, v[122:125] offset:64
	ds_write_b128 v199, v[126:129] offset:96
	ds_write_b128 v199, v[98:101] offset:128
	ds_write_b128 v199, v[102:105] offset:160
	ds_write_b128 v199, v[106:109] offset:192
	ds_write_b128 v199, v[110:113] offset:224
	v_lshl_add_u64 v[170:171], v[188:189], 0, v[144:145]
	v_lshlrev_b64 v[98:99], 12, v[168:169]
	v_lshl_add_u64 v[144:145], v[170:171], 0, v[98:99]
	v_or_b32_e32 v98, 4, v168
	v_ashrrev_i32_e32 v99, 31, v98
	v_lshlrev_b64 v[98:99], 12, v[98:99]
	v_lshl_add_u64 v[146:147], v[170:171], 0, v[98:99]
	v_or_b32_e32 v98, 8, v168
	v_ashrrev_i32_e32 v99, 31, v98
	v_lshlrev_b64 v[98:99], 12, v[98:99]
	v_lshl_add_u64 v[148:149], v[170:171], 0, v[98:99]
	v_or_b32_e32 v98, 12, v168
	v_ashrrev_i32_e32 v99, 31, v98
	v_lshlrev_b64 v[98:99], 12, v[98:99]
	v_lshl_add_u64 v[152:153], v[170:171], 0, v[98:99]
	v_or_b32_e32 v98, 16, v168
	v_ashrrev_i32_e32 v99, 31, v98
	v_lshlrev_b64 v[98:99], 12, v[98:99]
	v_lshl_add_u64 v[156:157], v[170:171], 0, v[98:99]
	v_or_b32_e32 v98, 20, v168
	v_ashrrev_i32_e32 v99, 31, v98
	v_lshlrev_b64 v[98:99], 12, v[98:99]
	v_lshl_add_u64 v[158:159], v[170:171], 0, v[98:99]
	v_or_b32_e32 v98, 24, v168
	v_ashrrev_i32_e32 v99, 31, v98
	v_lshlrev_b64 v[98:99], 12, v[98:99]
	v_lshl_add_u64 v[160:161], v[170:171], 0, v[98:99]
	v_or_b32_e32 v98, 28, v168
	v_ashrrev_i32_e32 v99, 31, v98
	v_lshlrev_b64 v[98:99], 12, v[98:99]
	global_load_dwordx4 v[126:129], v[144:145], off
	global_load_dwordx4 v[122:125], v[146:147], off
	v_lshl_add_u64 v[162:163], v[170:171], 0, v[98:99]
	global_load_dwordx4 v[118:121], v[148:149], off
	global_load_dwordx4 v[114:117], v[152:153], off
	global_load_dwordx4 v[110:113], v[156:157], off
	global_load_dwordx4 v[106:109], v[158:159], off
	global_load_dwordx4 v[102:105], v[160:161], off
	global_load_dwordx4 v[98:101], v[162:163], off
	ds_read_b128 v[172:175], v229
	v_or_b32_e32 v164, v138, v186
	v_mov_b32_e32 v165, v139
	v_lshl_add_u64 v[154:155], v[150:151], 0, v[164:165]
	s_mov_b64 s[2:3], -1
	s_waitcnt vmcnt(7) lgkmcnt(0)
	v_pk_fma_f32 v[128:129], v[136:137], v[174:175], v[128:129]
	v_pk_fma_f32 v[126:127], v[134:135], v[172:173], v[126:127]
	v_lshl_add_u64 v[172:173], v[154:155], 2, s[44:45]
	global_store_dwordx4 v[172:173], v[126:129], off
	s_cbranch_vccnz .LBB0_1006
	s_mov_b64 s[2:3], 0
